# S5a inner loop: all 8 LDS fragment reads issued up front with counted lgkmcnt waits (was one ds_read per MFMA behind lgkmcnt(0)); plus saddr LDS-DMA in all GEMM K-loops
# speedup vs baseline: 1.0027x; 1.0027x over previous
; #define LAS __attribute__((address_space(3)))
; __device__ __forceinline__ f32x4 mfma16(bf16x8 colfrag, bf16x8 rowfrag, f32x4 acc) { return __builtin_amdgcn_mfma_f32_16x16x32_bf16(colfrag, rowfrag, acc, 0, 0, 0); }
; __device__ void s5a_item(const Params& p, int item, LAS unsigned char* lds) {
;     ...
;         for (int nt = 0; nt < 8; ++nt) { f32x4 acc = (f32x4){0.f, 0.f, 0.f, 0.f};
; #pragma unroll
;             for (int ks = 0; ks < 8; ++ks) { const bf16x8 b = *(const LAS bf16x8*)(lds + (nt * 16 + fr) * 528 + (ks * 32 + fq * 8) * 2); acc = mfma16(b, a[ks], acc); }
;             *(f32x4*)(Xloc + ((size_t)(mt * 16 + fr) * 32 + g) * 128 + nt * 16 + 4 * fq) = acc; }
;     }
.LBB0_601:
	v_add_u32_e32 v39, s42, v44
	ds_read_b128 v[46:49], v39
	ds_read_b128 v[50:53], v39 offset:64
	ds_read_b128 v[100:103], v39 offset:128
	ds_read_b128 v[104:107], v39 offset:192
	ds_read_b128 v[108:111], v39 offset:256
	ds_read_b128 v[112:115], v39 offset:320
	ds_read_b128 v[116:119], v39 offset:384
	ds_read_b128 v[120:123], v39 offset:448
	s_addk_i32 s42, 0x2100
	s_cmp_lg_u32 s42, 0x10800
	s_waitcnt lgkmcnt(7)
	v_mfma_f32_16x16x32_bf16 v[46:49], v[46:49], v[2:5], 0
	s_waitcnt lgkmcnt(6)
	v_mfma_f32_16x16x32_bf16 v[46:49], v[50:53], v[6:9], v[46:49]
	s_waitcnt lgkmcnt(5)
	v_mfma_f32_16x16x32_bf16 v[46:49], v[100:103], v[10:13], v[46:49]
	s_waitcnt lgkmcnt(4)
	v_mfma_f32_16x16x32_bf16 v[46:49], v[104:107], v[14:17], v[46:49]
	s_waitcnt lgkmcnt(3)
	v_mfma_f32_16x16x32_bf16 v[46:49], v[108:111], v[18:21], v[46:49]
	s_waitcnt lgkmcnt(2)
	v_mfma_f32_16x16x32_bf16 v[46:49], v[112:115], v[22:25], v[46:49]
	s_waitcnt lgkmcnt(1)
	v_mfma_f32_16x16x32_bf16 v[46:49], v[116:119], v[26:29], v[46:49]
	s_waitcnt lgkmcnt(0)
	v_mfma_f32_16x16x32_bf16 v[46:49], v[120:123], v[30:33], v[46:49]
	s_nop 7
	global_store_dwordx4 v[40:41], v[46:49], off
	v_lshl_add_u64 v[40:41], v[40:41], 0, 64
	s_cbranch_scc1 .LBB0_601
	v_add_u32_e32 v0, 8, v0
	v_cmp_le_i32_e32 vcc, s30, v0
	s_or_b64 s[40:41], vcc, s[40:41]
	v_add_u32_e32 v38, 0x80, v38
	s_andn2_b64 exec, exec, s[40:41]
	s_cbranch_execnz .LBB0_598
	s_branch .LBB0_555
